# attention unit O stores write-through (sc1)
# speedup vs baseline: 1.0104x; 1.0020x over previous
.LBB0_370:
	s_or_b64 exec, exec, s[4:5]
	s_waitcnt lgkmcnt(0)
	ds_read_b128 v[34:37], v50 offset:49280
	ds_read_b128 v[38:41], v50 offset:49312
	s_lshl_b64 s[4:5], s[14:15], 11
	s_add_u32 s4, s52, s4
	s_addc_u32 s5, s53, s5
	s_waitcnt lgkmcnt(1)
	v_rcp_f32_e32 v0, v34
	s_lshl_b32 s6, s34, 1
	s_add_u32 s6, s4, s6
	v_rcp_f32_e32 v42, v35
	s_addc_u32 s7, s5, 0
	s_lshl_b32 s12, s27, 12
	v_rcp_f32_e32 v43, v36
	v_rcp_f32_e32 v44, v37
	s_waitcnt lgkmcnt(0)
	v_rcp_f32_e32 v45, v38
	ds_read_b128 v[34:37], v50 offset:49344
	v_rcp_f32_e32 v46, v39
	v_rcp_f32_e32 v47, v40
	v_rcp_f32_e32 v48, v41
	ds_read_b128 v[38:41], v50 offset:49376
	s_add_i32 s12, s12, 0
	v_lshlrev_b32_e32 v49, 9, v201
	v_lshlrev_b32_e32 v50, 1, v200
	v_mul_f32_e32 v18, v18, v0
	v_mul_f32_e32 v0, v2, v0
	v_add3_u32 v49, s12, v49, v50
	v_cvt_pk_bf16_f32 v0, v0, s0
	ds_write_b16 v49, v0 offset:51264
	v_mul_f32_e32 v0, v19, v42
	v_cvt_pk_bf16_f32 v0, v0, s0
	ds_write_b16 v49, v0 offset:51328
	v_mul_f32_e32 v0, v3, v42
	v_cvt_pk_bf16_f32 v0, v0, s0
	ds_write_b16 v49, v0 offset:51392
	v_mul_f32_e32 v0, v20, v43
	v_cvt_pk_bf16_f32 v0, v0, s0
	ds_write_b16 v49, v0 offset:51456
	v_mul_f32_e32 v0, v4, v43
	v_cvt_pk_bf16_f32 v0, v0, s0
	ds_write_b16 v49, v0 offset:51520
	v_mul_f32_e32 v0, v21, v44
	v_cvt_pk_bf16_f32 v0, v0, s0
	ds_write_b16 v49, v0 offset:51584
	v_mul_f32_e32 v0, v5, v44
	v_cvt_pk_bf16_f32 v0, v0, s0
	ds_write_b16 v49, v0 offset:51648
	v_mul_f32_e32 v0, v22, v45
	v_cvt_pk_bf16_f32 v0, v0, s0
	ds_write_b16 v49, v0 offset:52224
	v_mul_f32_e32 v0, v6, v45
	v_cvt_pk_bf16_f32 v0, v0, s0
	ds_write_b16 v49, v0 offset:52288
	v_mul_f32_e32 v0, v23, v46
	v_cvt_pk_bf16_f32 v0, v0, s0
	ds_write_b16 v49, v0 offset:52352
	v_mul_f32_e32 v0, v7, v46
	v_cvt_pk_bf16_f32 v0, v0, s0
	ds_write_b16 v49, v0 offset:52416
	v_mul_f32_e32 v0, v24, v47
	v_cvt_pk_bf16_f32 v0, v0, s0
	ds_write_b16 v49, v0 offset:52480
	v_mul_f32_e32 v0, v8, v47
	v_cvt_pk_bf16_f32 v0, v0, s0
	s_waitcnt lgkmcnt(13)
	v_rcp_f32_e32 v34, v34
	ds_write_b16 v49, v0 offset:52544
	v_mul_f32_e32 v0, v25, v48
	v_cvt_pk_bf16_f32 v0, v0, s0
	ds_write_b16 v49, v0 offset:52608
	v_mul_f32_e32 v0, v9, v48
	v_cvt_pk_bf16_f32 v0, v0, s0
	v_rcp_f32_e32 v35, v35
	ds_write_b16 v49, v0 offset:52672
	v_mul_f32_e32 v0, v26, v34
	v_cvt_pk_bf16_f32 v0, v0, s0
	ds_write_b16 v49, v0 offset:53248
	v_mul_f32_e32 v0, v10, v34
	v_cvt_pk_bf16_f32 v0, v0, s0
	v_rcp_f32_e32 v36, v36
	ds_write_b16 v49, v0 offset:53312
	v_mul_f32_e32 v0, v27, v35
	v_cvt_pk_bf16_f32 v0, v0, s0
	ds_write_b16 v49, v0 offset:53376
	v_mul_f32_e32 v0, v11, v35
	v_cvt_pk_bf16_f32 v0, v0, s0
	v_rcp_f32_e32 v37, v37
	ds_write_b16 v49, v0 offset:53440
	v_mul_f32_e32 v0, v28, v36
	v_cvt_pk_bf16_f32 v0, v0, s0
	ds_write_b16 v49, v0 offset:53504
	v_mul_f32_e32 v0, v12, v36
	v_cvt_pk_bf16_f32 v0, v0, s0
	s_waitcnt lgkmcnt(14)
	v_rcp_f32_e32 v38, v38
	ds_write_b16 v49, v0 offset:53568
	v_mul_f32_e32 v0, v29, v37
	v_cvt_pk_bf16_f32 v0, v0, s0
	ds_write_b16 v49, v0 offset:53632
	v_mul_f32_e32 v0, v13, v37
	v_cvt_pk_bf16_f32 v0, v0, s0
	v_rcp_f32_e32 v39, v39
	ds_write_b16 v49, v0 offset:53696
	v_mul_f32_e32 v0, v30, v38
	v_cvt_pk_bf16_f32 v0, v0, s0
	ds_write_b16 v49, v0 offset:54272
	v_mul_f32_e32 v0, v14, v38
	v_cvt_pk_bf16_f32 v0, v0, s0
	v_rcp_f32_e32 v40, v40
	ds_write_b16 v49, v0 offset:54336
	v_mul_f32_e32 v0, v31, v39
	v_cvt_pk_bf16_f32 v0, v0, s0
	ds_write_b16 v49, v0 offset:54400
	v_mul_f32_e32 v0, v15, v39
	v_cvt_pk_bf16_f32 v0, v0, s0
	v_rcp_f32_e32 v41, v41
	ds_write_b16 v49, v0 offset:54464
	v_mul_f32_e32 v0, v32, v40
	v_cvt_pk_bf16_f32 v0, v0, s0
	ds_write_b16 v49, v0 offset:54528
	v_mul_f32_e32 v0, v16, v40
	v_cvt_pk_bf16_f32 v0, v0, s0
	ds_write_b16 v49, v0 offset:54592
	v_mul_f32_e32 v0, v33, v41
	v_cvt_pk_bf16_f32 v0, v0, s0
	ds_write_b16 v49, v0 offset:54656
	v_mul_f32_e32 v0, v17, v41
	v_cvt_pk_bf16_f32 v0, v0, s0
	ds_write_b16 v49, v0 offset:54720
	v_lshlrev_b32_e32 v0, 1, v199
	v_cvt_pk_bf16_f32 v18, v18, s0
	v_and_b32_e32 v0, 0x70, v0
	ds_write_b16 v49, v18 offset:51200
	v_lshrrev_b32_e32 v10, 3, v198
	v_add_u32_e32 v11, s12, v0
	s_waitcnt lgkmcnt(0)
	v_lshl_add_u32 v2, v10, 7, v11
	s_lshl_b64 s[4:5], s[16:17], 11
	ds_read_b128 v[2:5], v2 offset:51200
	s_add_u32 s4, s6, s4
	s_addc_u32 s5, s7, s5
	v_lshl_add_u64 v[6:7], s[4:5], 0, v[0:1]
	v_lshlrev_b32_e32 v0, 11, v10
	v_lshl_add_u64 v[8:9], v[6:7], 0, v[0:1]
	v_or_b32_e32 v0, 8, v10
	s_waitcnt lgkmcnt(0)
	flat_store_dwordx4 v[8:9], v[2:5] sc1
	s_add_i32 s26, s26, 1
	s_cmp_eq_u32 s26, 3
	v_lshl_add_u32 v2, v0, 7, v11
	ds_read_b128 v[2:5], v2 offset:51200
	v_lshlrev_b32_e32 v0, 11, v0
	v_lshl_add_u64 v[8:9], v[6:7], 0, v[0:1]
	v_or_b32_e32 v0, 16, v10
	s_cselect_b64 s[4:5], -1, 0
	s_waitcnt lgkmcnt(0)
	flat_store_dwordx4 v[8:9], v[2:5] sc1
	s_nop 1
	v_lshl_add_u32 v2, v0, 7, v11
	ds_read_b128 v[2:5], v2 offset:51200
	v_lshlrev_b32_e32 v0, 11, v0
	v_lshl_add_u64 v[8:9], v[6:7], 0, v[0:1]
	v_or_b32_e32 v0, 24, v10
	s_waitcnt lgkmcnt(0)
	flat_store_dwordx4 v[8:9], v[2:5] sc1
	s_nop 1
	v_lshl_add_u32 v2, v0, 7, v11
	ds_read_b128 v[2:5], v2 offset:51200
	v_lshlrev_b32_e32 v0, 11, v0
	v_lshl_add_u64 v[6:7], v[6:7], 0, v[0:1]
	s_waitcnt lgkmcnt(0)
	flat_store_dwordx4 v[6:7], v[2:5] sc1
	s_waitcnt lgkmcnt(0)
	s_barrier
